# ssm_gen (P1 instance) KC loop hand-written: pairs of adjacent lags share the C/Bbar LDS operand reads; two accumulation chains, software-pipelined operand VALU
# speedup vs baseline: 1.0013x; 1.0013x over previous
; __device__ __forceinline__ void ssm_gen(LAS unsigned char* lds, const Args& a, int layer, int g, int j8) {
;     ...
;         const int wv = tid >> 6, l = tid & 63, col = l & 15, kq = l >> 4, part = kq & 1;
; #pragma unroll 1
;         for (int blk = wv; blk < 36; blk += 8) {
;             const int dir = blk < ndf ? 0 : 1, d = dir ? blk - ndf : blk;
;             f32x4 acc = {0.f, 0.f, 0.f, 0.f};
; #pragma unroll 8
;             for (int st = 0; st < 32; ++st) {
;                 const int p = 2 * st + (kq >> 1);
;                 const f32x2 c = CT[(dir * 64 + p) * 16 + col], w = PW[(dir * 33 + d) * 64 + p], bb = BB[(dir * 64 + p) * 16 + col];
.LBB0_366:
	s_or_b64 exec, exec, s[10:11]
	v_ashrrev_i32_e32 v13, 6, v12
	v_cmp_gt_i32_e32 vcc, 36, v13
	s_and_saveexec_b64 s[10:11], vcc
	s_cbranch_execz .LBB0_371
	v_and_b32_e32 v0, 16, v12
	v_cmp_eq_u32_e32 vcc, 0, v0
	v_lshlrev_b32_e32 v0, 4, v10
	v_and_b32_e32 v0, 0x300, v0
	v_readlane_b32 s1, v254, 49
	v_lshrrev_b32_e32 v16, 5, v10
	v_lshl_add_u32 v18, v16, 3, 0
	v_add3_u32 v14, s1, v0, v14
	v_readlane_b32 s1, v254, 50
	s_mov_b64 s[16:17], 0
	s_nop 0
	v_lshl_add_u32 v17, v11, 3, s1
	v_readfirstlane_b32 s7, v13
	v_lshl_add_u32 v35, v16, 7, v17
.Lkq_pair:
	s_lshl_b32 s1, s7, 1
	s_cmp_lt_i32 s1, s82
	s_cselect_b32 s8, 0, 1
	s_cselect_b32 s9, 0, s82
	s_sub_u32 s9, s1, s9
	s_mul_i32 s5, s8, 33
	s_add_u32 s5, s5, s9
	s_lshl_b32 s5, s5, 9
	v_add_u32_e32 v34, s5, v18
	s_lshl_b32 s38, s8, 13
	v_add_u32_e32 v33, s38, v35
	v_add_u32_e32 v32, 0x4000, v33
	s_lshl_b32 s39, s8, 5
	s_add_u32 s39, s39, s9
	v_mov_b32_e32 v0, 0
	v_mov_b32_e32 v1, 0
	v_mov_b32_e32 v2, 0
	v_mov_b32_e32 v3, 0
	v_mov_b32_e32 v4, 0
	v_mov_b32_e32 v5, 0
	v_mov_b32_e32 v6, 0
	v_mov_b32_e32 v7, 0
	s_mov_b32 s5, 0
; __device__ __forceinline__ void ssm_gen(LAS unsigned char* lds, const Args& a, int layer, int g, int j8) {
;     ...
;         for (int blk = wv; blk < 36; blk += 8) {
;             const int dir = blk < ndf ? 0 : 1, d = dir ? blk - ndf : blk;
;             f32x4 acc = {0.f, 0.f, 0.f, 0.f};
; #pragma unroll 8
;             for (int st = 0; st < 32; ++st) {
;                 const int p = 2 * st + (kq >> 1);
;                 const f32x2 c = CT[(dir * 64 + p) * 16 + col], w = PW[(dir * 33 + d) * 64 + p], bb = BB[(dir * 64 + p) * 16 + col];
;                 const float av = part ? -(c.x * w.y + c.y * w.x) : (c.x * w.x - c.y * w.y);
;                 const float bv = part ? bb.y : bb.x;
;                 acc = __builtin_amdgcn_mfma_f32_16x16x4f32(av, bv, acc, 0, 0, 0);
;             }
; #pragma unroll
;             for (int i = 0; i < 4; ++i) KC[(dir * 32 + d) * KCS + (4 * kq + i) * 16 + col] = acc[i];
;         }
.Lkq_trip:
	ds_read2_b64 v[40:43], v32 offset0:0 offset1:32
	ds_read2_b64 v[56:59], v33 offset0:0 offset1:32
	ds_read2_b64 v[72:75], v34 offset0:0 offset1:2
	ds_read2_b64 v[88:91], v34 offset0:64 offset1:66
	ds_read2_b64 v[44:47], v32 offset0:64 offset1:96
	ds_read2_b64 v[60:63], v33 offset0:64 offset1:96
	ds_read2_b64 v[76:79], v34 offset0:4 offset1:6
	ds_read2_b64 v[92:95], v34 offset0:68 offset1:70
	ds_read2_b64 v[48:51], v32 offset0:128 offset1:160
	ds_read2_b64 v[64:67], v33 offset0:128 offset1:160
	ds_read2_b64 v[80:83], v34 offset0:8 offset1:10
	ds_read2_b64 v[96:99], v34 offset0:72 offset1:74
	ds_read2_b64 v[52:55], v32 offset0:192 offset1:224
	ds_read2_b64 v[68:71], v33 offset0:192 offset1:224
	ds_read2_b64 v[84:87], v34 offset0:12 offset1:14
	ds_read2_b64 v[100:103], v34 offset0:76 offset1:78
	s_waitcnt lgkmcnt(12)
	v_pk_mul_f32 v[20:21], v[40:41], v[72:73] op_sel:[0,1] op_sel_hi:[1,0]
	v_pk_mul_f32 v[22:23], v[40:41], v[72:73]
	v_add_f32_e32 v20, v20, v21
	v_sub_f32_e32 v22, v22, v23
	v_cndmask_b32_e64 v104, -v20, v22, vcc
	v_cndmask_b32_e32 v106, v57, v56, vcc
	v_pk_mul_f32 v[24:25], v[40:41], v[88:89] op_sel:[0,1] op_sel_hi:[1,0]
	v_pk_mul_f32 v[26:27], v[40:41], v[88:89]
	v_add_f32_e32 v24, v24, v25
	v_sub_f32_e32 v26, v26, v27
	v_cndmask_b32_e64 v105, -v24, v26, vcc
	s_nop 1
	v_mfma_f32_16x16x4_f32 v[0:3], v104, v106, v[0:3]
	v_pk_mul_f32 v[20:21], v[42:43], v[74:75] op_sel:[0,1] op_sel_hi:[1,0]
	v_pk_mul_f32 v[22:23], v[42:43], v[74:75]
	v_add_f32_e32 v20, v20, v21
	v_sub_f32_e32 v22, v22, v23
	v_cndmask_b32_e64 v107, -v20, v22, vcc
	v_cndmask_b32_e32 v109, v59, v58, vcc
	v_mfma_f32_16x16x4_f32 v[4:7], v105, v106, v[4:7]
	v_pk_mul_f32 v[24:25], v[42:43], v[90:91] op_sel:[0,1] op_sel_hi:[1,0]
	v_pk_mul_f32 v[26:27], v[42:43], v[90:91]
	v_add_f32_e32 v24, v24, v25
	v_sub_f32_e32 v26, v26, v27
	v_cndmask_b32_e64 v108, -v24, v26, vcc
	v_mfma_f32_16x16x4_f32 v[0:3], v107, v109, v[0:3]
	s_waitcnt lgkmcnt(8)
	v_pk_mul_f32 v[20:21], v[44:45], v[76:77] op_sel:[0,1] op_sel_hi:[1,0]
	v_pk_mul_f32 v[22:23], v[44:45], v[76:77]
	v_add_f32_e32 v20, v20, v21
	v_sub_f32_e32 v22, v22, v23
	v_cndmask_b32_e64 v104, -v20, v22, vcc
	v_cndmask_b32_e32 v106, v61, v60, vcc
	v_mfma_f32_16x16x4_f32 v[4:7], v108, v109, v[4:7]
	v_pk_mul_f32 v[24:25], v[44:45], v[92:93] op_sel:[0,1] op_sel_hi:[1,0]
	v_pk_mul_f32 v[26:27], v[44:45], v[92:93]
	v_add_f32_e32 v24, v24, v25
	v_sub_f32_e32 v26, v26, v27
	v_cndmask_b32_e64 v105, -v24, v26, vcc
	v_mfma_f32_16x16x4_f32 v[0:3], v104, v106, v[0:3]
	v_pk_mul_f32 v[20:21], v[46:47], v[78:79] op_sel:[0,1] op_sel_hi:[1,0]
	v_pk_mul_f32 v[22:23], v[46:47], v[78:79]
	v_add_f32_e32 v20, v20, v21
	v_sub_f32_e32 v22, v22, v23
	v_cndmask_b32_e64 v107, -v20, v22, vcc
	v_cndmask_b32_e32 v109, v63, v62, vcc
	v_mfma_f32_16x16x4_f32 v[4:7], v105, v106, v[4:7]
	v_pk_mul_f32 v[24:25], v[46:47], v[94:95] op_sel:[0,1] op_sel_hi:[1,0]
	v_pk_mul_f32 v[26:27], v[46:47], v[94:95]
	v_add_f32_e32 v24, v24, v25
	v_sub_f32_e32 v26, v26, v27
	v_cndmask_b32_e64 v108, -v24, v26, vcc
	v_mfma_f32_16x16x4_f32 v[0:3], v107, v109, v[0:3]
	s_waitcnt lgkmcnt(4)
	v_pk_mul_f32 v[20:21], v[48:49], v[80:81] op_sel:[0,1] op_sel_hi:[1,0]
	v_pk_mul_f32 v[22:23], v[48:49], v[80:81]
	v_add_f32_e32 v20, v20, v21
	v_sub_f32_e32 v22, v22, v23
	v_cndmask_b32_e64 v104, -v20, v22, vcc
	v_cndmask_b32_e32 v106, v65, v64, vcc
	v_mfma_f32_16x16x4_f32 v[4:7], v108, v109, v[4:7]
	v_pk_mul_f32 v[24:25], v[48:49], v[96:97] op_sel:[0,1] op_sel_hi:[1,0]
	v_pk_mul_f32 v[26:27], v[48:49], v[96:97]
	v_add_f32_e32 v24, v24, v25
	v_sub_f32_e32 v26, v26, v27
	v_cndmask_b32_e64 v105, -v24, v26, vcc
	v_mfma_f32_16x16x4_f32 v[0:3], v104, v106, v[0:3]
	v_pk_mul_f32 v[20:21], v[50:51], v[82:83] op_sel:[0,1] op_sel_hi:[1,0]
	v_pk_mul_f32 v[22:23], v[50:51], v[82:83]
	v_add_f32_e32 v20, v20, v21
	v_sub_f32_e32 v22, v22, v23
	v_cndmask_b32_e64 v107, -v20, v22, vcc
	v_cndmask_b32_e32 v109, v67, v66, vcc
	v_mfma_f32_16x16x4_f32 v[4:7], v105, v106, v[4:7]
	v_pk_mul_f32 v[24:25], v[50:51], v[98:99] op_sel:[0,1] op_sel_hi:[1,0]
	v_pk_mul_f32 v[26:27], v[50:51], v[98:99]
	v_add_f32_e32 v24, v24, v25
	v_sub_f32_e32 v26, v26, v27
	v_cndmask_b32_e64 v108, -v24, v26, vcc
	v_mfma_f32_16x16x4_f32 v[0:3], v107, v109, v[0:3]
	s_waitcnt lgkmcnt(0)
	v_pk_mul_f32 v[20:21], v[52:53], v[84:85] op_sel:[0,1] op_sel_hi:[1,0]
	v_pk_mul_f32 v[22:23], v[52:53], v[84:85]
	v_add_f32_e32 v20, v20, v21
	v_sub_f32_e32 v22, v22, v23
	v_cndmask_b32_e64 v104, -v20, v22, vcc
	v_cndmask_b32_e32 v106, v69, v68, vcc
	v_mfma_f32_16x16x4_f32 v[4:7], v108, v109, v[4:7]
	v_pk_mul_f32 v[24:25], v[52:53], v[100:101] op_sel:[0,1] op_sel_hi:[1,0]
	v_pk_mul_f32 v[26:27], v[52:53], v[100:101]
	v_add_f32_e32 v24, v24, v25
	v_sub_f32_e32 v26, v26, v27
	v_cndmask_b32_e64 v105, -v24, v26, vcc
	v_mfma_f32_16x16x4_f32 v[0:3], v104, v106, v[0:3]
	v_pk_mul_f32 v[20:21], v[54:55], v[86:87] op_sel:[0,1] op_sel_hi:[1,0]
	v_pk_mul_f32 v[22:23], v[54:55], v[86:87]
	v_add_f32_e32 v20, v20, v21
	v_sub_f32_e32 v22, v22, v23
	v_cndmask_b32_e64 v107, -v20, v22, vcc
	v_cndmask_b32_e32 v109, v71, v70, vcc
	v_mfma_f32_16x16x4_f32 v[4:7], v105, v106, v[4:7]
	v_pk_mul_f32 v[24:25], v[54:55], v[102:103] op_sel:[0,1] op_sel_hi:[1,0]
	v_pk_mul_f32 v[26:27], v[54:55], v[102:103]
	v_add_f32_e32 v24, v24, v25
	v_sub_f32_e32 v26, v26, v27
	v_cndmask_b32_e64 v108, -v24, v26, vcc
	v_mfma_f32_16x16x4_f32 v[0:3], v107, v109, v[0:3]
	v_mfma_f32_16x16x4_f32 v[4:7], v108, v109, v[4:7]
	v_add_u32_e32 v32, 0x800, v32
	v_add_u32_e32 v33, 0x800, v33
	v_add_u32_e32 v34, 0x80, v34
	s_add_u32 s5, s5, 1
	s_cmp_lt_u32 s5, 4
	s_cbranch_scc1 .Lkq_trip
	s_mul_i32 s1, s39, 0x410
	s_nop 7
	v_add_u32_e32 v20, s1, v14
	v_add_u32_e32 v21, 0x410, v20
	s_nop 1
	ds_write2_b32 v20, v0, v1 offset1:16
	ds_write2_b32 v20, v2, v3 offset0:32 offset1:48
	ds_write2_b32 v21, v4, v5 offset1:16
	ds_write2_b32 v21, v6, v7 offset0:32 offset1:48
	s_add_u32 s7, s7, 8
	s_cmp_lt_u32 s7, 18
	s_cbranch_scc1 .Lkq_pair
